# readout phase: norm gains loaded once before the row loop, next-row prefetch no longer drained
# baseline (speedup 1.0000x reference)
; DI void unpack8(const u32x4 w, float (&f)[8]) { f[0] = bf_lo(w.x); f[1] = bf_hi(w.x); f[2] = bf_lo(w.y); f[3] = bf_hi(w.y); f[4] = bf_lo(w.z); f[5] = bf_hi(w.z); f[6] = bf_lo(w.w); f[7] = bf_hi(w.w); }
; DI float silu(float x) { return x * frcp(1.0f + __expf(-x)); }
; DI void phase_readout(int l, int nrows, int wv) {
;     ...
;     auto row_load = [&](int r, RowIn& R) { const bf16* prow = F.PROJ + (size_t)r * INW; const bf16* osc = (const bf16*)F.OSC;
; #pragma unroll
;         for (int c = 0; c < 2; ++c) { const int e0 = c * 512 + F.lane * 8;
;             R.a[c] = *(const u32x4*)(osc + (size_t)r * DC + e0); R.b[c] = *(const u32x4*)(osc + ((size_t)NTOK + r) * DC + e0);
;             R.og[c] = *(const u32x4*)(prow + C_OG + e0); } };
;     auto row_compute = [&](int r, const RowIn& R) {
; #pragma unroll
;         for (int c = 0; c < 2; ++c) {
;             const int e0 = c * 512 + F.lane * 8;
;             float o[8], og[8], yb[8]; float ss = 0.f;
;             { float fa[8], fb[8]; unpack8(R.a[c], fa); unpack8(R.b[c], fb);
; #pragma unroll
;               for (int j = 0; j < 8; ++j) o[j] = fa[j] + fb[j]; }
; #pragma unroll
;             for (int j = 0; j < 8; ++j) ss += o[j] * o[j];
;             ss += __shfl_xor(ss, 1); ss += __shfl_xor(ss, 2); ss += __shfl_xor(ss, 4); ss += __shfl_xor(ss, 8);
;             const float rs = rsqrtf(ss * (1.0f / DK) + LN_EPS);
;             unpack8(R.og[c], og);
; #pragma unroll
;             for (int j = 0; j < 8; ++j) yb[j] = o[j] * rs * ng[(e0 + j) & (DK - 1)] * silu(og[j]);
.LBB0_564:
	s_andn2_b64 vcc, exec, s[0:1]
	s_cbranch_vccnz .LBB0_626
	s_waitcnt vmcnt(0)
	v_mov_b32_e32 v0, v129
	v_readlane_b32 s0, v253, 54
	v_mbcnt_lo_u32_b32 v0, -1, v0
	v_mbcnt_hi_u32_b32 v24, -1, v0
	s_mov_b32 s2, s88
	v_mov_b32_e32 v0, s0
	ds_read_b64 v[0:1], v0
	s_waitcnt lgkmcnt(0)
	v_mov_b32_e32 v0, s79
	ds_read_b64 v[0:1], v0
	v_readlane_b32 s3, v252, 0
	s_add_i32 s2, s2, s3
	v_readlane_b32 s3, v254, 12
	s_cmp_ge_i32 s2, s15
	s_waitcnt lgkmcnt(0)
	v_readfirstlane_b32 s0, v0
	v_mov_b32_e32 v0, s3
	v_readfirstlane_b32 s1, v1
	ds_read_b64 v[0:1], v0
	s_movk_i32 s16, 0x3000
	s_waitcnt lgkmcnt(0)
	v_readfirstlane_b32 s3, v1
	v_readfirstlane_b32 s4, v0
	s_cbranch_scc1 .LBB0_574
	s_load_dword s11, s[90:91], 0x0
	s_add_u32 s6, s0, 0x1ec00000
	s_addc_u32 s7, s1, 0
	s_add_u32 s8, s0, 0x39c00000
	s_addc_u32 s9, s1, 0
	s_lshl_b32 s76, s92, 7
	s_waitcnt lgkmcnt(0)
	s_lshl_b32 s10, s11, 3
	s_lshl_b64 s[12:13], s[76:77], 2
	s_add_u32 s4, s4, s12
	s_addc_u32 s5, s3, s13
	s_ashr_i32 s3, s2, 31
	s_mul_i32 s12, s2, 0x6000
	s_mul_hi_i32 s13, s2, 0x6000
	s_add_u32 s12, s6, s12
	s_addc_u32 s13, s7, s13
	s_lshl_b64 s[14:15], s[2:3], 11
	v_lshlrev_b32_e32 v26, 3, v24
	s_add_u32 s14, s8, s14
	v_ashrrev_i32_e32 v27, 31, v26
	s_addc_u32 s15, s9, s15
	v_lshlrev_b64 v[52:53], 1, v[26:27]
	v_lshl_add_u64 v[4:5], s[14:15], 0, v[52:53]
	s_mov_b32 s3, 0x2400000
	v_add_co_u32_e32 v8, vcc, s3, v4
	v_lshl_add_u64 v[0:1], s[12:13], 0, v[52:53]
	s_nop 0
	v_addc_co_u32_e32 v9, vcc, 0, v5, vcc
	s_mov_b64 s[14:15], 0x2400000
	s_mov_b64 s[12:13], 0x3800
	v_add_co_u32_e32 v16, vcc, s16, v0
	v_lshl_add_u64 v[12:13], v[4:5], 0, s[14:15]
	v_lshl_add_u64 v[20:21], v[0:1], 0, s[12:13]
	v_addc_co_u32_e32 v17, vcc, 0, v1, vcc
	global_load_dwordx4 v[0:3], v[4:5], off
	s_nop 0
	global_load_dwordx4 v[4:7], v[4:5], off offset:1024
	s_nop 0
	global_load_dwordx4 v[8:11], v[8:9], off
	s_nop 0
	global_load_dwordx4 v[12:15], v[12:13], off offset:1024
	s_nop 0
	global_load_dwordx4 v[16:19], v[16:17], off offset:2048
	s_nop 0
	global_load_dwordx4 v[20:23], v[20:21], off offset:1024
	v_and_b32_e32 v28, 64, v239
	v_xor_b32_e32 v25, 1, v239
	v_add_u32_e32 v28, 64, v28
	v_cmp_lt_i32_e32 vcc, v25, v28
	v_lshlrev_b32_e32 v24, 5, v24
	v_and_b32_e32 v128, 0x1e0, v24
	v_cndmask_b32_e32 v25, v239, v25, vcc
	v_lshlrev_b32_e32 v64, 2, v25
	v_xor_b32_e32 v25, 2, v239
	v_cmp_lt_i32_e32 vcc, v25, v28
	v_readlane_b32 s15, v254, 35
	v_lshl_add_u64 v[54:55], s[4:5], 0, v[128:129]
	global_load_dwordx4 v[130:133], v[54:55], off
	global_load_dwordx4 v[134:137], v[54:55], off offset:16
	v_cndmask_b32_e32 v25, v239, v25, vcc
	v_lshlrev_b32_e32 v65, 2, v25
	v_xor_b32_e32 v25, 4, v239
	v_cmp_lt_i32_e32 vcc, v25, v28
	s_lshl_b32 s11, s11, 4
	s_nop 0
	v_cndmask_b32_e32 v25, v239, v25, vcc
	v_lshlrev_b32_e32 v66, 2, v25
	v_xor_b32_e32 v25, 8, v239
	v_cmp_lt_i32_e32 vcc, v25, v28
	s_nop 1
	v_cndmask_b32_e32 v25, v239, v25, vcc
	v_lshlrev_b32_e32 v67, 2, v25
	v_lshl_add_u64 v[24:25], s[0:1], 0, v[26:27]
	s_mov_b64 s[0:1], 0x15c00000
	v_lshl_add_u64 v[56:57], v[24:25], 0, s[0:1]
	s_branch .LBB0_569
.LBB0_567:
	v_mov_b32_e32 v68, v130
	v_mov_b32_e32 v69, v131
	v_mov_b32_e32 v70, v132
	v_mov_b32_e32 v71, v133
	v_mov_b32_e32 v48, v134
	v_mov_b32_e32 v49, v135
	v_mov_b32_e32 v50, v136
	v_mov_b32_e32 v51, v137
	v_lshlrev_b32_e32 v86, 16, v40
	v_mul_f32_e32 v87, 0xbfb8aa3b, v86
	v_and_b32_e32 v73, 0xffff0000, v24
	v_and_b32_e32 v75, 0xffff0000, v32
	v_lshlrev_b32_e32 v63, 16, v25
	v_lshlrev_b32_e32 v77, 16, v33
	v_and_b32_e32 v62, 0xffff0000, v25
	v_and_b32_e32 v76, 0xffff0000, v33
	v_and_b32_e32 v72, 0xffff0000, v28
	v_and_b32_e32 v74, 0xffff0000, v36
	v_lshlrev_b32_e32 v103, 16, v29
	v_lshlrev_b32_e32 v105, 16, v37
	v_and_b32_e32 v102, 0xffff0000, v29
	v_and_b32_e32 v104, 0xffff0000, v37
	v_exp_f32_e32 v87, v87
	v_lshlrev_b32_e32 v59, 16, v24
	v_lshlrev_b32_e32 v61, 16, v32
	v_lshlrev_b32_e32 v79, 16, v26
	v_lshlrev_b32_e32 v81, 16, v34
	v_and_b32_e32 v78, 0xffff0000, v26
	v_and_b32_e32 v80, 0xffff0000, v34
	v_lshlrev_b32_e32 v83, 16, v27
	v_lshlrev_b32_e32 v85, 16, v35
	v_and_b32_e32 v82, 0xffff0000, v27
	v_and_b32_e32 v84, 0xffff0000, v35
	v_lshlrev_b32_e32 v58, 16, v28
	v_lshlrev_b32_e32 v60, 16, v36
	v_lshlrev_b32_e32 v107, 16, v30
	v_lshlrev_b32_e32 v109, 16, v38
	v_and_b32_e32 v106, 0xffff0000, v30
	v_and_b32_e32 v108, 0xffff0000, v38
	v_pk_add_f32 v[76:77], v[76:77], v[62:63]
	v_pk_add_f32 v[62:63], v[104:105], v[102:103]
	v_pk_add_f32 v[72:73], v[74:75], v[72:73]
	v_lshlrev_b32_e32 v111, 16, v31
	v_lshlrev_b32_e32 v113, 16, v39
	v_and_b32_e32 v110, 0xffff0000, v31
	v_and_b32_e32 v112, 0xffff0000, v39
	v_pk_add_f32 v[78:79], v[80:81], v[78:79]
	v_pk_add_f32 v[80:81], v[84:85], v[82:83]
	v_pk_add_f32 v[82:83], v[60:61], v[58:59]
	v_pk_add_f32 v[60:61], v[108:109], v[106:107]
	v_pk_mul_f32 v[74:75], v[76:77], v[76:77]
	v_pk_mul_f32 v[104:105], v[62:63], v[62:63]
	v_pk_mul_f32 v[106:107], v[72:73], v[72:73]
	v_pk_add_f32 v[58:59], v[112:113], v[110:111]
	v_pk_fma_f32 v[106:107], v[82:83], v[82:83], v[106:107]
	v_mov_b32_e32 v112, v105
	v_mov_b32_e32 v113, v75
	v_pk_mul_f32 v[84:85], v[78:79], v[78:79]
	v_pk_mul_f32 v[108:109], v[60:61], v[60:61]
	v_mov_b32_e32 v105, v74
	v_pk_add_f32 v[106:107], v[112:113], v[106:107]
	v_add_f32_e32 v75, 1.0, v87
	v_mov_b32_e32 v74, v109
	v_pk_add_f32 v[104:105], v[104:105], v[106:107]
	v_rcp_f32_e32 v106, v75
	v_mov_b32_e32 v75, v85
	v_pk_mul_f32 v[102:103], v[80:81], v[80:81]
	v_pk_mul_f32 v[110:111], v[58:59], v[58:59]
	v_pk_add_f32 v[74:75], v[74:75], v[104:105]
	v_mov_b32_e32 v109, v84
	v_pk_add_f32 v[74:75], v[108:109], v[74:75]
	v_mov_b32_e32 v84, v111
	v_mov_b32_e32 v85, v103
	v_pk_add_f32 v[74:75], v[84:85], v[74:75]
	v_mov_b32_e32 v111, v102
	v_pk_add_f32 v[74:75], v[110:111], v[74:75]
	ds_bpermute_b32 v85, v64, v75
	ds_bpermute_b32 v84, v64, v74
	v_and_b32_e32 v88, 0xffff0000, v40
	v_lshlrev_b32_e32 v94, 16, v42
	v_mul_f32_e32 v89, 0xbfb8aa3b, v88
	v_mul_f32_e32 v95, 0xbfb8aa3b, v94
	s_waitcnt lgkmcnt(0)
; DI unsigned pk4_fp8(float a, float b, float c, float d) { int w = 0; w = __builtin_amdgcn_cvt_pk_fp8_f32(clamp448(a), clamp448(b), w, false); w = __builtin_amdgcn_cvt_pk_fp8_f32(clamp448(c), clamp448(d), w, true); return (unsigned)w; }
; DI void unpack8(const u32x4 w, float (&f)[8]) { f[0] = bf_lo(w.x); f[1] = bf_hi(w.x); f[2] = bf_lo(w.y); f[3] = bf_hi(w.y); f[4] = bf_lo(w.z); f[5] = bf_hi(w.z); f[6] = bf_lo(w.w); f[7] = bf_hi(w.w); }
; DI float silu(float x) { return x * frcp(1.0f + __expf(-x)); }
; DI void phase_readout(int l, int nrows, int wv) {
;     ...
;     auto row_compute = [&](int r, const RowIn& R) {
; #pragma unroll
;         for (int c = 0; c < 2; ++c) {
;             const int e0 = c * 512 + F.lane * 8;
;             float o[8], og[8], yb[8]; float ss = 0.f;
;             { float fa[8], fb[8]; unpack8(R.a[c], fa); unpack8(R.b[c], fb);
; #pragma unroll
;               for (int j = 0; j < 8; ++j) o[j] = fa[j] + fb[j]; }
; #pragma unroll
;             for (int j = 0; j < 8; ++j) ss += o[j] * o[j];
;             ss += __shfl_xor(ss, 1); ss += __shfl_xor(ss, 2); ss += __shfl_xor(ss, 4); ss += __shfl_xor(ss, 8);
;             const float rs = rsqrtf(ss * (1.0f / DK) + LN_EPS);
;             unpack8(R.og[c], og);
; #pragma unroll
;             for (int j = 0; j < 8; ++j) yb[j] = o[j] * rs * ng[(e0 + j) & (DK - 1)] * silu(og[j]);
;             *(u32x2*)((unsigned char*)F.H + (size_t)r * D + DC + e0) = (u32x2){pk4_fp8(yb[0] * SA8_Y, yb[1] * SA8_Y, yb[2] * SA8_Y, yb[3] * SA8_Y), pk4_fp8(yb[4] * SA8_Y, yb[5] * SA8_Y, yb[6] * SA8_Y, yb[7] * SA8_Y)};
;         } };
	v_pk_add_f32 v[74:75], v[74:75], v[84:85]
	ds_bpermute_b32 v85, v65, v75
	ds_bpermute_b32 v84, v65, v74
	v_exp_f32_e32 v89, v89
	v_exp_f32_e32 v95, v95
	v_lshlrev_b32_e32 v98, 16, v43
	v_mov_b32_e32 v107, v68
	s_waitcnt lgkmcnt(0)
	v_pk_add_f32 v[74:75], v[74:75], v[84:85]
	ds_bpermute_b32 v85, v66, v75
	ds_bpermute_b32 v84, v66, v74
	v_add_f32_e32 v87, 1.0, v89
	v_rcp_f32_e32 v68, v87
	v_add_f32_e32 v87, 1.0, v95
	v_rcp_f32_e32 v102, v87
	s_waitcnt lgkmcnt(0)
	v_pk_add_f32 v[74:75], v[74:75], v[84:85]
	ds_bpermute_b32 v85, v67, v75
	ds_bpermute_b32 v84, v67, v74
	v_mul_f32_e32 v87, 0xbfb8aa3b, v98
	s_brev_b32 s2, 60
	v_lshlrev_b32_e32 v90, 16, v41
	v_exp_f32_e32 v87, v87
	s_waitcnt lgkmcnt(0)
	v_pk_add_f32 v[74:75], v[74:75], v[84:85]
	v_and_b32_e32 v92, 0xffff0000, v41
	v_pk_fma_f32 v[74:75], v[74:75], s[2:3], v[206:207] op_sel_hi:[1,0,0]
	v_mul_f32_e32 v91, 0xbfb8aa3b, v90
	v_mul_f32_e32 v84, 0x4b800000, v75
	v_cmp_gt_f32_e32 vcc, s14, v75
	v_and_b32_e32 v96, 0xffff0000, v42
	v_mul_f32_e32 v93, 0xbfb8aa3b, v92
	v_exp_f32_e32 v91, v91
	v_cndmask_b32_e32 v75, v75, v84, vcc
	v_exp_f32_e32 v93, v93
	v_mov_b32_e32 v103, v48
	v_mul_f32_e32 v48, 0xbfb8aa3b, v96
	v_rsq_f32_e32 v75, v75
	v_and_b32_e32 v100, 0xffff0000, v43
	v_exp_f32_e32 v48, v48
	v_add_f32_e32 v87, 1.0, v87
	v_rcp_f32_e32 v104, v87
	v_mul_f32_e32 v87, 0xbfb8aa3b, v100
	v_add_f32_e32 v89, 1.0, v91
	v_exp_f32_e32 v87, v87
	v_rcp_f32_e32 v112, v89
	v_mov_b32_e32 v113, v70
	v_add_f32_e32 v70, 1.0, v93
	v_mul_f32_e32 v84, 0x45800000, v75
	v_rcp_f32_e32 v70, v70
	v_add_f32_e32 v48, 1.0, v48
	v_cndmask_b32_e32 v75, v75, v84, vcc
	v_rcp_f32_e32 v48, v48
	v_mul_f32_e32 v89, v73, v75
	v_mov_b32_e32 v105, v50
	v_add_f32_e32 v50, 1.0, v87
	v_pk_mul_f32 v[68:69], v[68:69], v[88:89]
	v_mul_f32_e32 v91, v77, v75
	v_rcp_f32_e32 v50, v50
	v_mul_f32_e32 v73, v68, v69
	v_pk_mul_f32 v[68:69], v[112:113], v[90:91]
	v_mul_f32_e32 v93, v76, v75
	v_mul_f32_e32 v77, v68, v69
	v_pk_mul_f32 v[68:69], v[70:71], v[92:93]
	v_mul_f32_e32 v95, v79, v75
	v_mul_f32_e32 v97, v78, v75
	v_mul_f32_e32 v87, v83, v75
	v_mul_f32_e32 v70, v68, v69
	v_pk_mul_f32 v[68:69], v[102:103], v[94:95]
	v_pk_mul_f32 v[48:49], v[48:49], v[96:97]
	v_mul_f32_e32 v99, v81, v75
	v_pk_mul_f32 v[84:85], v[106:107], v[86:87]
	v_mul_f32_e32 v68, v68, v69
	v_mul_f32_e32 v69, v48, v49
	v_pk_mul_f32 v[48:49], v[104:105], v[98:99]
	v_mul_f32_e32 v101, v80, v75
	v_mul_f32_e32 v83, v84, v85
	v_mul_f32_e32 v71, v48, v49
	v_pk_mul_f32 v[48:49], v[50:51], v[100:101]
	v_mul_f32_e32 v51, 0x41000000, v77
	v_mul_f32_e32 v50, v48, v49
	v_mul_f32_e32 v48, 0x41000000, v83
	v_mul_f32_e32 v49, 0x41000000, v73
	v_med3_f32 v73, v48, s33, v238
	v_med3_f32 v49, v49, s33, v238
	v_mov_b32_e32 v48, v129
	v_cvt_pk_fp8_f32 v48, v73, v49
	v_mul_f32_e32 v49, 0x41000000, v70
	v_med3_f32 v51, v51, s33, v238
	v_med3_f32 v49, v49, s33, v238
	v_cvt_pk_fp8_f32 v48, v51, v49 op_sel:[0,0,1]
	v_mul_f32_e32 v49, 0x41000000, v68
	v_mul_f32_e32 v51, 0x41000000, v69
	v_med3_f32 v69, v49, s33, v238
	v_med3_f32 v51, v51, s33, v238
	v_mov_b32_e32 v49, v129
	v_cvt_pk_fp8_f32 v49, v69, v51
	v_mul_f32_e32 v68, 0x41000000, v71
	v_mul_f32_e32 v50, 0x41000000, v50
	v_med3_f32 v51, v68, s33, v238
	v_med3_f32 v50, v50, s33, v238
	v_cvt_pk_fp8_f32 v49, v51, v50 op_sel:[0,0,1]
	s_ashr_i32 s1, s0, 31
	s_lshl_b64 s[2:3], s[0:1], 11
	v_lshl_add_u64 v[76:77], v[56:57], 0, s[2:3]
	global_store_dwordx2 v[76:77], v[48:49], off offset:1024
	v_mov_b32_e32 v48, v130
	v_mov_b32_e32 v49, v131
	v_mov_b32_e32 v50, v132
	v_mov_b32_e32 v51, v133
	s_nop 0
	v_mov_b32_e32 v68, v134
	v_mov_b32_e32 v69, v135
	v_mov_b32_e32 v70, v136
	v_mov_b32_e32 v71, v137
	v_mul_f32_e32 v73, 0x4b800000, v74
	v_cmp_gt_f32_e32 vcc, s14, v74
	v_and_b32_e32 v78, 0xffff0000, v44
	v_mul_f32_e32 v81, 0xbfb8aa3b, v78
	v_cndmask_b32_e32 v73, v74, v73, vcc
	v_rsq_f32_e32 v73, v73
	v_exp_f32_e32 v81, v81
	v_lshlrev_b32_e32 v80, 16, v45
	v_and_b32_e32 v84, 0xffff0000, v45
	v_mul_f32_e32 v74, 0x45800000, v73
	v_cndmask_b32_e32 v73, v73, v74, vcc
	v_lshlrev_b32_e32 v74, 16, v44
	v_mul_f32_e32 v75, 0xbfb8aa3b, v74
	v_exp_f32_e32 v79, v75
	v_mul_f32_e32 v75, v82, v73
	v_mul_f32_e32 v85, v62, v73
	v_lshlrev_b32_e32 v86, 16, v46
	v_add_f32_e32 v79, 1.0, v79
	v_rcp_f32_e32 v82, v79
	v_mul_f32_e32 v79, v72, v73
	v_and_b32_e32 v88, 0xffff0000, v46
	v_mul_f32_e32 v87, v61, v73
	v_mul_f32_e32 v89, v60, v73
	v_lshlrev_b32_e32 v90, 16, v47
	v_and_b32_e32 v92, 0xffff0000, v47
	v_mul_f32_e32 v91, v59, v73
	v_mul_f32_e32 v93, v58, v73
	s_add_i32 s2, s0, s10
	s_cmp_ge_i32 s2, s15
	s_cselect_b64 s[4:5], -1, 0
	v_mov_b32_e32 v83, v48
	v_add_f32_e32 v48, 1.0, v81
	v_rcp_f32_e32 v48, v48
	v_mul_f32_e32 v81, v63, v73
	v_pk_mul_f32 v[74:75], v[82:83], v[74:75]
	v_pk_mul_f32 v[48:49], v[48:49], v[78:79]
	s_nop 0
	v_mul_f32_e32 v72, v48, v49
	v_mul_f32_e32 v48, 0xbfb8aa3b, v80
	v_exp_f32_e32 v48, v48
	v_mul_f32_e32 v49, 0xbfb8aa3b, v84
	v_exp_f32_e32 v63, v49
	v_mov_b32_e32 v49, v50
	v_add_f32_e32 v48, 1.0, v48
	v_rcp_f32_e32 v48, v48
	v_add_f32_e32 v50, 1.0, v63
	v_rcp_f32_e32 v50, v50
	v_mul_f32_e32 v74, v74, v75
	v_pk_mul_f32 v[48:49], v[48:49], v[80:81]
	s_nop 0
	v_mul_f32_e32 v63, v48, v49
	v_pk_mul_f32 v[48:49], v[50:51], v[84:85]
	v_mul_f32_e32 v61, 0x41000000, v63
	v_mul_f32_e32 v50, v48, v49
	v_mul_f32_e32 v48, 0xbfb8aa3b, v86
	v_exp_f32_e32 v48, v48
	v_mul_f32_e32 v49, 0xbfb8aa3b, v88
	v_exp_f32_e32 v51, v49
	v_mov_b32_e32 v49, v68
	v_add_f32_e32 v48, 1.0, v48
	v_rcp_f32_e32 v48, v48
	v_add_f32_e32 v51, 1.0, v51
	v_rcp_f32_e32 v68, v51
	v_pk_mul_f32 v[48:49], v[48:49], v[86:87]
	s_nop 0
	v_mul_f32_e32 v51, v48, v49
	v_pk_mul_f32 v[48:49], v[68:69], v[88:89]
	s_nop 0
	v_mul_f32_e32 v60, v48, v49
	v_mul_f32_e32 v48, 0xbfb8aa3b, v90
	v_exp_f32_e32 v48, v48
	v_mul_f32_e32 v49, 0xbfb8aa3b, v92
	v_exp_f32_e32 v59, v49
	v_mov_b32_e32 v49, v70
	v_add_f32_e32 v48, 1.0, v48
	v_rcp_f32_e32 v48, v48
	v_add_f32_e32 v59, 1.0, v59
	v_rcp_f32_e32 v70, v59
	v_pk_mul_f32 v[48:49], v[48:49], v[90:91]
	s_nop 0
	v_mul_f32_e32 v59, v48, v49
	v_pk_mul_f32 v[48:49], v[70:71], v[92:93]
	s_nop 0
	v_mul_f32_e32 v58, v48, v49
	v_mul_f32_e32 v48, 0x41000000, v74
	v_mul_f32_e32 v49, 0x41000000, v72
	v_med3_f32 v62, v48, s33, v238
	v_med3_f32 v49, v49, s33, v238
	v_mov_b32_e32 v48, v129
	v_cvt_pk_fp8_f32 v48, v62, v49
	v_mul_f32_e32 v49, 0x41000000, v50
	v_med3_f32 v50, v61, s33, v238
	v_med3_f32 v49, v49, s33, v238
	v_cvt_pk_fp8_f32 v48, v50, v49 op_sel:[0,0,1]
	v_mul_f32_e32 v49, 0x41000000, v51
	v_mul_f32_e32 v50, 0x41000000, v60
	v_mul_f32_e32 v51, 0x41000000, v59
	v_med3_f32 v59, v49, s33, v238
	v_med3_f32 v50, v50, s33, v238
	v_mov_b32_e32 v49, v129
	v_cvt_pk_fp8_f32 v49, v59, v50
	v_mul_f32_e32 v50, 0x41000000, v58
	v_med3_f32 v51, v51, s33, v238
	v_med3_f32 v50, v50, s33, v238
	v_cvt_pk_fp8_f32 v49, v51, v50 op_sel:[0,0,1]
	global_store_dwordx2 v[76:77], v[48:49], off offset:1536

; DI void phase_readout(int l, int nrows, int wv) {
;     ...
;     auto row_load = [&](int r, RowIn& R) { const bf16* prow = F.PROJ + (size_t)r * INW; const bf16* osc = (const bf16*)F.OSC;
; #pragma unroll
;         for (int c = 0; c < 2; ++c) { const int e0 = c * 512 + F.lane * 8;
;             R.a[c] = *(const u32x4*)(osc + (size_t)r * DC + e0); R.b[c] = *(const u32x4*)(osc + ((size_t)NTOK + r) * DC + e0);
;             R.og[c] = *(const u32x4*)(prow + C_OG + e0); } };
;     ...
;         const int n1 = r + NGW, n2 = r + 2 * NGW;
;         if (n1 < nrows) row_load(n1, RB);
.LBB0_569:
	s_add_i32 s0, s2, s10
	s_cmp_lt_i32 s0, s15
	s_cselect_b64 s[4:5], -1, 0
	s_cmp_ge_i32 s0, s15
	s_cbranch_scc1 .Lro_nopf1
	s_ashr_i32 s1, s0, 31
	s_mul_i32 s12, s0, 0x6000
	s_mul_hi_i32 s3, s0, 0x6000
	s_add_u32 s12, s6, s12
	s_addc_u32 s13, s7, s3
	s_lshl_b64 s[14:15], s[0:1], 11
	s_add_u32 s14, s8, s14
	s_addc_u32 s15, s9, s15
	v_lshl_add_u64 v[28:29], s[14:15], 0, v[52:53]
	v_add_co_u32_e32 v32, vcc, 0x2400000, v28
	v_lshl_add_u64 v[24:25], s[12:13], 0, v[52:53]
	s_nop 0
	v_addc_co_u32_e32 v33, vcc, 0, v29, vcc
	s_mov_b64 s[14:15], 0x2400000
	s_mov_b64 s[12:13], 0x3800
	v_add_co_u32_e32 v40, vcc, 0x3000, v24
	v_lshl_add_u64 v[36:37], v[28:29], 0, s[14:15]
	v_lshl_add_u64 v[44:45], v[24:25], 0, s[12:13]
	v_addc_co_u32_e32 v41, vcc, 0, v25, vcc
	global_load_dwordx4 v[24:27], v[28:29], off
	s_nop 0
	global_load_dwordx4 v[28:31], v[28:29], off offset:1024
	s_nop 0
	global_load_dwordx4 v[32:35], v[32:33], off
	s_nop 0
	global_load_dwordx4 v[36:39], v[36:37], off offset:1024
	s_nop 0
	global_load_dwordx4 v[40:43], v[40:41], off offset:2048
	s_nop 0
	global_load_dwordx4 v[44:47], v[44:45], off offset:1024
	v_readlane_b32 s15, v254, 35
	s_waitcnt vmcnt(6)
	s_branch .LBB0_571

; DI unsigned pk4_fp8(float a, float b, float c, float d) { int w = 0; w = __builtin_amdgcn_cvt_pk_fp8_f32(clamp448(a), clamp448(b), w, false); w = __builtin_amdgcn_cvt_pk_fp8_f32(clamp448(c), clamp448(d), w, true); return (unsigned)w; }
; DI void unpack8(const u32x4 w, float (&f)[8]) { f[0] = bf_lo(w.x); f[1] = bf_hi(w.x); f[2] = bf_lo(w.y); f[3] = bf_hi(w.y); f[4] = bf_lo(w.z); f[5] = bf_hi(w.z); f[6] = bf_lo(w.w); f[7] = bf_hi(w.w); }
; DI float silu(float x) { return x * frcp(1.0f + __expf(-x)); }
; DI void phase_readout(int l, int nrows, int wv) {
;     ...
;     auto row_compute = [&](int r, const RowIn& R) {
; #pragma unroll
;         for (int c = 0; c < 2; ++c) {
;             const int e0 = c * 512 + F.lane * 8;
;             float o[8], og[8], yb[8]; float ss = 0.f;
;             { float fa[8], fb[8]; unpack8(R.a[c], fa); unpack8(R.b[c], fb);
; #pragma unroll
;               for (int j = 0; j < 8; ++j) o[j] = fa[j] + fb[j]; }
; #pragma unroll
;             for (int j = 0; j < 8; ++j) ss += o[j] * o[j];
;             ss += __shfl_xor(ss, 1); ss += __shfl_xor(ss, 2); ss += __shfl_xor(ss, 4); ss += __shfl_xor(ss, 8);
;             const float rs = rsqrtf(ss * (1.0f / DK) + LN_EPS);
;             unpack8(R.og[c], og);
; #pragma unroll
;             for (int j = 0; j < 8; ++j) yb[j] = o[j] * rs * ng[(e0 + j) & (DK - 1)] * silu(og[j]);
;             *(u32x2*)((unsigned char*)F.H + (size_t)r * D + DC + e0) = (u32x2){pk4_fp8(yb[0] * SA8_Y, yb[1] * SA8_Y, yb[2] * SA8_Y, yb[3] * SA8_Y), pk4_fp8(yb[4] * SA8_Y, yb[5] * SA8_Y, yb[6] * SA8_Y, yb[7] * SA8_Y)};
;         } };
.LBB0_571:
	v_mov_b32_e32 v68, v130
	v_mov_b32_e32 v69, v131
	v_mov_b32_e32 v70, v132
	v_mov_b32_e32 v71, v133
	v_mov_b32_e32 v48, v134
	v_mov_b32_e32 v49, v135
	v_mov_b32_e32 v50, v136
	v_mov_b32_e32 v51, v137
	v_lshlrev_b32_e32 v86, 16, v16
	v_mul_f32_e32 v87, 0xbfb8aa3b, v86
	v_and_b32_e32 v73, 0xffff0000, v8
	v_and_b32_e32 v75, 0xffff0000, v0
	v_lshlrev_b32_e32 v63, 16, v9
	v_lshlrev_b32_e32 v77, 16, v1
	v_and_b32_e32 v62, 0xffff0000, v9
	v_and_b32_e32 v76, 0xffff0000, v1
	v_and_b32_e32 v72, 0xffff0000, v12
	v_and_b32_e32 v74, 0xffff0000, v4
	v_lshlrev_b32_e32 v103, 16, v13
	v_lshlrev_b32_e32 v105, 16, v5
	v_and_b32_e32 v102, 0xffff0000, v13
	v_and_b32_e32 v104, 0xffff0000, v5
	v_exp_f32_e32 v87, v87
	v_lshlrev_b32_e32 v59, 16, v8
	v_lshlrev_b32_e32 v61, 16, v0
	v_lshlrev_b32_e32 v79, 16, v10
	v_lshlrev_b32_e32 v81, 16, v2
	v_and_b32_e32 v78, 0xffff0000, v10
	v_and_b32_e32 v80, 0xffff0000, v2
	v_lshlrev_b32_e32 v83, 16, v11
	v_lshlrev_b32_e32 v85, 16, v3
	v_and_b32_e32 v82, 0xffff0000, v11
	v_and_b32_e32 v84, 0xffff0000, v3
	v_lshlrev_b32_e32 v58, 16, v12
	v_lshlrev_b32_e32 v60, 16, v4
	v_lshlrev_b32_e32 v107, 16, v14
	v_lshlrev_b32_e32 v109, 16, v6
	v_and_b32_e32 v106, 0xffff0000, v14
	v_and_b32_e32 v108, 0xffff0000, v6
	v_pk_add_f32 v[76:77], v[76:77], v[62:63]
	v_pk_add_f32 v[62:63], v[104:105], v[102:103]
	v_pk_add_f32 v[72:73], v[74:75], v[72:73]
	v_lshlrev_b32_e32 v111, 16, v15
	v_lshlrev_b32_e32 v113, 16, v7
	v_and_b32_e32 v110, 0xffff0000, v15
	v_and_b32_e32 v112, 0xffff0000, v7
	v_pk_add_f32 v[78:79], v[80:81], v[78:79]
	v_pk_add_f32 v[80:81], v[84:85], v[82:83]
	v_pk_add_f32 v[82:83], v[60:61], v[58:59]
	v_pk_add_f32 v[60:61], v[108:109], v[106:107]
	v_pk_mul_f32 v[74:75], v[76:77], v[76:77]
	v_pk_mul_f32 v[104:105], v[62:63], v[62:63]
	v_pk_mul_f32 v[106:107], v[72:73], v[72:73]
	v_pk_add_f32 v[58:59], v[112:113], v[110:111]
	v_pk_fma_f32 v[106:107], v[82:83], v[82:83], v[106:107]
	v_mov_b32_e32 v112, v105
	v_mov_b32_e32 v113, v75
	v_pk_mul_f32 v[84:85], v[78:79], v[78:79]
	v_pk_mul_f32 v[108:109], v[60:61], v[60:61]
	v_mov_b32_e32 v105, v74
	v_pk_add_f32 v[106:107], v[112:113], v[106:107]
	v_add_f32_e32 v75, 1.0, v87
	v_mov_b32_e32 v74, v109
	v_pk_add_f32 v[104:105], v[104:105], v[106:107]
	v_rcp_f32_e32 v106, v75
	v_mov_b32_e32 v75, v85
	v_pk_mul_f32 v[102:103], v[80:81], v[80:81]
	v_pk_mul_f32 v[110:111], v[58:59], v[58:59]
	v_pk_add_f32 v[74:75], v[74:75], v[104:105]
	v_mov_b32_e32 v109, v84
	v_pk_add_f32 v[74:75], v[108:109], v[74:75]
	v_mov_b32_e32 v84, v111
	v_mov_b32_e32 v85, v103
	v_pk_add_f32 v[74:75], v[84:85], v[74:75]
	v_mov_b32_e32 v111, v102
	v_pk_add_f32 v[74:75], v[110:111], v[74:75]
	ds_bpermute_b32 v85, v64, v75
	ds_bpermute_b32 v84, v64, v74
	v_and_b32_e32 v88, 0xffff0000, v16
	v_lshlrev_b32_e32 v94, 16, v18
	v_mul_f32_e32 v89, 0xbfb8aa3b, v88
	v_mul_f32_e32 v95, 0xbfb8aa3b, v94
	s_waitcnt lgkmcnt(0)
	v_pk_add_f32 v[74:75], v[74:75], v[84:85]
	ds_bpermute_b32 v85, v65, v75
	ds_bpermute_b32 v84, v65, v74
	v_exp_f32_e32 v89, v89
	v_exp_f32_e32 v95, v95
	v_lshlrev_b32_e32 v98, 16, v19
	v_mov_b32_e32 v107, v68
	s_waitcnt lgkmcnt(0)
	v_pk_add_f32 v[74:75], v[74:75], v[84:85]
	ds_bpermute_b32 v85, v66, v75
	ds_bpermute_b32 v84, v66, v74
	v_add_f32_e32 v87, 1.0, v89
	v_rcp_f32_e32 v68, v87
	v_add_f32_e32 v87, 1.0, v95
	v_rcp_f32_e32 v102, v87
	s_waitcnt lgkmcnt(0)
	v_pk_add_f32 v[74:75], v[74:75], v[84:85]
	ds_bpermute_b32 v85, v67, v75
	ds_bpermute_b32 v84, v67, v74
	v_mul_f32_e32 v87, 0xbfb8aa3b, v98
	s_brev_b32 s12, 60
	v_lshlrev_b32_e32 v90, 16, v17
	v_exp_f32_e32 v87, v87
	s_waitcnt lgkmcnt(0)
	v_pk_add_f32 v[74:75], v[74:75], v[84:85]
	s_mov_b32 s14, 0x800000
	v_pk_fma_f32 v[74:75], v[74:75], s[12:13], v[206:207] op_sel_hi:[1,0,0]
	v_and_b32_e32 v92, 0xffff0000, v17
	v_mul_f32_e32 v91, 0xbfb8aa3b, v90
	v_mul_f32_e32 v84, 0x4b800000, v75
	v_cmp_gt_f32_e32 vcc, s14, v75
	v_and_b32_e32 v96, 0xffff0000, v18
	v_mul_f32_e32 v93, 0xbfb8aa3b, v92
	v_exp_f32_e32 v91, v91
	v_cndmask_b32_e32 v75, v75, v84, vcc
	v_exp_f32_e32 v93, v93
	v_mov_b32_e32 v103, v48
	v_mul_f32_e32 v48, 0xbfb8aa3b, v96
	v_rsq_f32_e32 v75, v75
	v_and_b32_e32 v100, 0xffff0000, v19
	v_exp_f32_e32 v48, v48
	v_add_f32_e32 v87, 1.0, v87
	v_rcp_f32_e32 v104, v87
	v_mul_f32_e32 v87, 0xbfb8aa3b, v100
	v_add_f32_e32 v89, 1.0, v91
	v_exp_f32_e32 v87, v87
	v_rcp_f32_e32 v112, v89
	v_mov_b32_e32 v113, v70
	v_add_f32_e32 v70, 1.0, v93
	v_mul_f32_e32 v84, 0x45800000, v75
	v_rcp_f32_e32 v70, v70
	v_add_f32_e32 v48, 1.0, v48
	v_cndmask_b32_e32 v75, v75, v84, vcc
	v_rcp_f32_e32 v48, v48
	v_mul_f32_e32 v89, v73, v75
	v_mov_b32_e32 v105, v50
	v_add_f32_e32 v50, 1.0, v87
	v_pk_mul_f32 v[68:69], v[68:69], v[88:89]
	v_mul_f32_e32 v91, v77, v75
	v_rcp_f32_e32 v50, v50
	v_mul_f32_e32 v73, v68, v69
	v_pk_mul_f32 v[68:69], v[112:113], v[90:91]
	v_mul_f32_e32 v93, v76, v75
	v_mul_f32_e32 v77, v68, v69
	v_pk_mul_f32 v[68:69], v[70:71], v[92:93]
	v_mul_f32_e32 v95, v79, v75
	v_mul_f32_e32 v97, v78, v75
	v_mul_f32_e32 v87, v83, v75
	v_mul_f32_e32 v70, v68, v69
	v_pk_mul_f32 v[68:69], v[102:103], v[94:95]
	v_pk_mul_f32 v[48:49], v[48:49], v[96:97]
	v_mul_f32_e32 v99, v81, v75
	v_pk_mul_f32 v[84:85], v[106:107], v[86:87]
	v_mul_f32_e32 v68, v68, v69
	v_mul_f32_e32 v69, v48, v49
	v_pk_mul_f32 v[48:49], v[104:105], v[98:99]
	v_mul_f32_e32 v101, v80, v75
	v_mul_f32_e32 v83, v84, v85
	v_mul_f32_e32 v71, v48, v49
	v_pk_mul_f32 v[48:49], v[50:51], v[100:101]
	v_mul_f32_e32 v51, 0x41000000, v77
; DI unsigned pk4_fp8(float a, float b, float c, float d) { int w = 0; w = __builtin_amdgcn_cvt_pk_fp8_f32(clamp448(a), clamp448(b), w, false); w = __builtin_amdgcn_cvt_pk_fp8_f32(clamp448(c), clamp448(d), w, true); return (unsigned)w; }
; DI void unpack8(const u32x4 w, float (&f)[8]) { f[0] = bf_lo(w.x); f[1] = bf_hi(w.x); f[2] = bf_lo(w.y); f[3] = bf_hi(w.y); f[4] = bf_lo(w.z); f[5] = bf_hi(w.z); f[6] = bf_lo(w.w); f[7] = bf_hi(w.w); }
; DI float silu(float x) { return x * frcp(1.0f + __expf(-x)); }
; DI void phase_readout(int l, int nrows, int wv) {
;     ...
;     auto row_compute = [&](int r, const RowIn& R) {
; #pragma unroll
;         for (int c = 0; c < 2; ++c) {
;             const int e0 = c * 512 + F.lane * 8;
;             float o[8], og[8], yb[8]; float ss = 0.f;
;             { float fa[8], fb[8]; unpack8(R.a[c], fa); unpack8(R.b[c], fb);
; #pragma unroll
;               for (int j = 0; j < 8; ++j) o[j] = fa[j] + fb[j]; }
; #pragma unroll
;             for (int j = 0; j < 8; ++j) ss += o[j] * o[j];
;             ss += __shfl_xor(ss, 1); ss += __shfl_xor(ss, 2); ss += __shfl_xor(ss, 4); ss += __shfl_xor(ss, 8);
;             const float rs = rsqrtf(ss * (1.0f / DK) + LN_EPS);
;             unpack8(R.og[c], og);
; #pragma unroll
;             for (int j = 0; j < 8; ++j) yb[j] = o[j] * rs * ng[(e0 + j) & (DK - 1)] * silu(og[j]);
;             *(u32x2*)((unsigned char*)F.H + (size_t)r * D + DC + e0) = (u32x2){pk4_fp8(yb[0] * SA8_Y, yb[1] * SA8_Y, yb[2] * SA8_Y, yb[3] * SA8_Y), pk4_fp8(yb[4] * SA8_Y, yb[5] * SA8_Y, yb[6] * SA8_Y, yb[7] * SA8_Y)};
;         } };
;     ...
;     while (r < nrows) {
;         const int n1 = r + NGW, n2 = r + 2 * NGW;
;         if (n1 < nrows) row_load(n1, RB);
;         row_compute(r, RA);
;         if (n1 >= nrows) break;
;         if (n2 < nrows) row_load(n2, RA);
;         row_compute(n1, RB);
;         r = n2;
;     }
	v_mul_f32_e32 v50, v48, v49
	v_mul_f32_e32 v48, 0x41000000, v83
	v_mul_f32_e32 v49, 0x41000000, v73
	v_med3_f32 v73, v48, s33, v238
	v_med3_f32 v49, v49, s33, v238
	v_mov_b32_e32 v48, v129
	v_cvt_pk_fp8_f32 v48, v73, v49
	v_mul_f32_e32 v49, 0x41000000, v70
	v_med3_f32 v51, v51, s33, v238
	v_med3_f32 v49, v49, s33, v238
	v_cvt_pk_fp8_f32 v48, v51, v49 op_sel:[0,0,1]
	v_mul_f32_e32 v49, 0x41000000, v68
	v_mul_f32_e32 v51, 0x41000000, v69
	v_med3_f32 v69, v49, s33, v238
	v_med3_f32 v51, v51, s33, v238
	v_mov_b32_e32 v49, v129
	v_cvt_pk_fp8_f32 v49, v69, v51
	v_mul_f32_e32 v68, 0x41000000, v71
	v_mul_f32_e32 v50, 0x41000000, v50
	v_med3_f32 v51, v68, s33, v238
	v_med3_f32 v50, v50, s33, v238
	v_cvt_pk_fp8_f32 v49, v51, v50 op_sel:[0,0,1]
	s_ashr_i32 s3, s2, 31
	s_lshl_b64 s[12:13], s[2:3], 11
	v_lshl_add_u64 v[76:77], v[56:57], 0, s[12:13]
	global_store_dwordx2 v[76:77], v[48:49], off offset:1024
	v_mov_b32_e32 v48, v130
	v_mov_b32_e32 v49, v131
	v_mov_b32_e32 v50, v132
	v_mov_b32_e32 v51, v133
	s_nop 0
	v_mov_b32_e32 v68, v134
	v_mov_b32_e32 v69, v135
	v_mov_b32_e32 v70, v136
	v_mov_b32_e32 v71, v137
	v_mul_f32_e32 v73, 0x4b800000, v74
	v_cmp_gt_f32_e32 vcc, s14, v74
	v_and_b32_e32 v78, 0xffff0000, v20
	v_mul_f32_e32 v81, 0xbfb8aa3b, v78
	v_cndmask_b32_e32 v73, v74, v73, vcc
	v_rsq_f32_e32 v73, v73
	v_exp_f32_e32 v81, v81
	v_lshlrev_b32_e32 v80, 16, v21
	v_and_b32_e32 v84, 0xffff0000, v21
	v_mul_f32_e32 v74, 0x45800000, v73
	v_cndmask_b32_e32 v73, v73, v74, vcc
	v_lshlrev_b32_e32 v74, 16, v20
	v_mul_f32_e32 v75, 0xbfb8aa3b, v74
	v_exp_f32_e32 v79, v75
	v_mul_f32_e32 v75, v82, v73
	v_mul_f32_e32 v85, v62, v73
	v_lshlrev_b32_e32 v86, 16, v22
	v_add_f32_e32 v79, 1.0, v79
	v_rcp_f32_e32 v82, v79
	v_mul_f32_e32 v79, v72, v73
	v_and_b32_e32 v88, 0xffff0000, v22
	v_mul_f32_e32 v87, v61, v73
	v_mul_f32_e32 v89, v60, v73
	v_lshlrev_b32_e32 v90, 16, v23
	v_and_b32_e32 v92, 0xffff0000, v23
	v_mul_f32_e32 v91, v59, v73
	v_mul_f32_e32 v93, v58, v73
	s_andn2_b64 vcc, exec, s[4:5]
	s_mov_b64 s[4:5], -1
	v_mov_b32_e32 v83, v48
	v_add_f32_e32 v48, 1.0, v81
	v_rcp_f32_e32 v48, v48
	v_mul_f32_e32 v81, v63, v73
	v_pk_mul_f32 v[74:75], v[82:83], v[74:75]
	v_pk_mul_f32 v[48:49], v[48:49], v[78:79]
	s_nop 0
	v_mul_f32_e32 v72, v48, v49
	v_mul_f32_e32 v48, 0xbfb8aa3b, v80
	v_exp_f32_e32 v48, v48
	v_mul_f32_e32 v49, 0xbfb8aa3b, v84
	v_exp_f32_e32 v63, v49
	v_mov_b32_e32 v49, v50
	v_add_f32_e32 v48, 1.0, v48
	v_rcp_f32_e32 v48, v48
	v_add_f32_e32 v50, 1.0, v63
	v_rcp_f32_e32 v50, v50
	v_mul_f32_e32 v74, v74, v75
	v_pk_mul_f32 v[48:49], v[48:49], v[80:81]
	s_nop 0
	v_mul_f32_e32 v63, v48, v49
	v_pk_mul_f32 v[48:49], v[50:51], v[84:85]
	v_mul_f32_e32 v61, 0x41000000, v63
	v_mul_f32_e32 v50, v48, v49
	v_mul_f32_e32 v48, 0xbfb8aa3b, v86
	v_exp_f32_e32 v48, v48
	v_mul_f32_e32 v49, 0xbfb8aa3b, v88
	v_exp_f32_e32 v51, v49
	v_mov_b32_e32 v49, v68
	v_add_f32_e32 v48, 1.0, v48
	v_rcp_f32_e32 v48, v48
	v_add_f32_e32 v51, 1.0, v51
	v_rcp_f32_e32 v68, v51
	v_pk_mul_f32 v[48:49], v[48:49], v[86:87]
	s_nop 0
	v_mul_f32_e32 v51, v48, v49
	v_pk_mul_f32 v[48:49], v[68:69], v[88:89]
	s_nop 0
	v_mul_f32_e32 v60, v48, v49
	v_mul_f32_e32 v48, 0xbfb8aa3b, v90
	v_exp_f32_e32 v48, v48
	v_mul_f32_e32 v49, 0xbfb8aa3b, v92
	v_exp_f32_e32 v59, v49
	v_mov_b32_e32 v49, v70
	v_add_f32_e32 v48, 1.0, v48
	v_rcp_f32_e32 v48, v48
	v_add_f32_e32 v59, 1.0, v59
	v_rcp_f32_e32 v70, v59
	v_pk_mul_f32 v[48:49], v[48:49], v[90:91]
	s_nop 0
	v_mul_f32_e32 v59, v48, v49
	v_pk_mul_f32 v[48:49], v[70:71], v[92:93]
	s_nop 0
	v_mul_f32_e32 v58, v48, v49
	v_mul_f32_e32 v48, 0x41000000, v74
	v_mul_f32_e32 v49, 0x41000000, v72
	v_med3_f32 v62, v48, s33, v238
	v_med3_f32 v49, v49, s33, v238
	v_mov_b32_e32 v48, v129
	v_cvt_pk_fp8_f32 v48, v62, v49
	v_mul_f32_e32 v49, 0x41000000, v50
	v_med3_f32 v50, v61, s33, v238
	v_med3_f32 v49, v49, s33, v238
	v_cvt_pk_fp8_f32 v48, v50, v49 op_sel:[0,0,1]
	v_mul_f32_e32 v49, 0x41000000, v51
	v_mul_f32_e32 v50, 0x41000000, v60
	v_mul_f32_e32 v51, 0x41000000, v59
	v_med3_f32 v59, v49, s33, v238
	v_med3_f32 v50, v50, s33, v238
	v_mov_b32_e32 v49, v129
	v_cvt_pk_fp8_f32 v49, v59, v50
	v_mul_f32_e32 v50, 0x41000000, v58
	v_med3_f32 v51, v51, s33, v238
	v_med3_f32 v50, v50, s33, v238
	v_cvt_pk_fp8_f32 v49, v51, v50 op_sel:[0,0,1]
	global_store_dwordx2 v[76:77], v[48:49], off offset:1536
	s_cbranch_vccnz .LBB0_568
	s_add_i32 s2, s11, s2
	s_cmp_ge_i32 s2, s15
	s_cbranch_scc1 .Lro_nopf2
	s_ashr_i32 s3, s2, 31
	s_mul_i32 s4, s2, 0x6000
	s_mul_hi_i32 s1, s2, 0x6000
	s_add_u32 s4, s6, s4
	s_addc_u32 s5, s7, s1
	s_lshl_b64 s[2:3], s[2:3], 11
	s_add_u32 s2, s8, s2
	s_addc_u32 s3, s9, s3
	v_lshl_add_u64 v[4:5], s[2:3], 0, v[52:53]
	v_add_co_u32_e32 v8, vcc, 0x2400000, v4
	s_mov_b64 s[2:3], 0x2400000
	s_nop 0
	v_addc_co_u32_e32 v9, vcc, 0, v5, vcc
	v_lshl_add_u64 v[0:1], s[4:5], 0, v[52:53]
	v_lshl_add_u64 v[12:13], v[4:5], 0, s[2:3]
	s_mov_b64 s[2:3], 0x3800
	v_add_co_u32_e32 v16, vcc, 0x3000, v0
	v_lshl_add_u64 v[20:21], v[0:1], 0, s[2:3]
	s_nop 0
	v_addc_co_u32_e32 v17, vcc, 0, v1, vcc
	global_load_dwordx4 v[0:3], v[4:5], off
	s_nop 0
	global_load_dwordx4 v[4:7], v[4:5], off offset:1024
	s_nop 0
	global_load_dwordx4 v[8:11], v[8:9], off
	s_nop 0
	global_load_dwordx4 v[12:15], v[12:13], off offset:1024
	s_nop 0
	global_load_dwordx4 v[16:19], v[16:17], off offset:2048
	s_nop 0
	global_load_dwordx4 v[20:23], v[20:21], off offset:1024
	s_waitcnt vmcnt(6)
	s_branch .LBB0_567
.Lro_nopf2:
	s_waitcnt vmcnt(0)
	s_branch .LBB0_567
